# nt also on the f32 new-cache tail stores of the layer-0 projection epilogue (outputs never re-read)
# speedup vs baseline: 1.0040x; 1.0040x over previous
.LBB0_219:
	s_and_b64 vcc, s[10:11], exec
	s_cselect_b32 s54, 9, 4
	s_add_u32 s62, s30, s62
	v_lshlrev_b32_e32 v131, s54, v185
	s_addc_u32 s63, s31, s63
	v_or_b32_e32 v174, s42, v131
	v_ashrrev_i32_e32 v133, 31, v132
	s_and_b64 s[10:11], s[10:11], exec
	v_lshl_add_u64 v[136:137], s[62:63], 0, v[174:175]
	v_lshlrev_b64 v[132:133], 12, v[132:133]
	s_cselect_b32 s57, 4, 6
	v_lshl_add_u64 v[136:137], v[136:137], 0, v[132:133]
	v_lshlrev_b32_e32 v132, s57, v1
	v_mov_b32_e32 v133, v175
	v_lshl_add_u64 v[136:137], v[136:137], 0, v[132:133]
	v_cmp_ne_u64_e32 vcc, 0, v[134:135]
	v_cvt_pk_bf16_f32 v138, v126, v127
	v_cvt_pk_bf16_f32 v139, v128, v129
	v_cvt_pk_bf16_f32 v140, v122, v123
	v_cvt_pk_bf16_f32 v141, v124, v125
	global_store_dwordx4 v[136:137], v[138:141], off
	s_and_saveexec_b64 s[10:11], vcc
	s_cbranch_execz .LBB0_221
	global_store_dwordx4 v[134:135], v[126:129], off nt
	global_store_dwordx4 v[134:135], v[122:125], off offset:16 nt
.LBB0_221:
	s_or_b64 exec, exec, s[10:11]
	v_lshl_add_u64 v[140:141], v[136:137], 0, s[60:61]
	v_cvt_pk_bf16_f32 v136, v118, v119
	v_cvt_pk_bf16_f32 v137, v120, v121
	v_cvt_pk_bf16_f32 v138, v114, v115
	v_cvt_pk_bf16_f32 v139, v116, v117
	global_store_dwordx4 v[140:141], v[136:139], off
	s_and_saveexec_b64 s[10:11], vcc
	s_cbranch_execz .LBB0_223
	global_store_dwordx4 v[134:135], v[118:121], off offset:512 nt
	global_store_dwordx4 v[134:135], v[114:117], off offset:528 nt

.LBB0_227:
	s_add_u32 s62, s30, s62
	s_addc_u32 s63, s31, s63
	v_ashrrev_i32_e32 v135, 31, v134
	v_lshl_add_u64 v[138:139], s[62:63], 0, v[174:175]
	v_lshlrev_b64 v[134:135], 12, v[134:135]
	v_lshl_add_u64 v[138:139], v[138:139], 0, v[134:135]
	v_lshlrev_b32_e32 v134, s57, v197
	v_mov_b32_e32 v135, v175
	v_lshl_add_u64 v[138:139], v[138:139], 0, v[134:135]
	v_cmp_ne_u64_e32 vcc, 0, v[136:137]
	v_cvt_pk_bf16_f32 v140, v110, v111
	v_cvt_pk_bf16_f32 v141, v112, v113
	v_cvt_pk_bf16_f32 v142, v106, v107
	v_cvt_pk_bf16_f32 v143, v108, v109
	global_store_dwordx4 v[138:139], v[140:143], off
	s_and_saveexec_b64 s[62:63], vcc
	s_cbranch_execz .LBB0_229
	global_store_dwordx4 v[136:137], v[110:113], off nt
	global_store_dwordx4 v[136:137], v[106:109], off offset:16 nt
.LBB0_229:
	s_or_b64 exec, exec, s[62:63]
	v_lshl_add_u64 v[142:143], v[138:139], 0, s[60:61]
	v_cvt_pk_bf16_f32 v138, v102, v103
	v_cvt_pk_bf16_f32 v139, v104, v105
	v_cvt_pk_bf16_f32 v140, v98, v99
	v_cvt_pk_bf16_f32 v141, v100, v101
	global_store_dwordx4 v[142:143], v[138:141], off
	s_and_saveexec_b64 s[60:61], vcc
	s_cbranch_execz .LBB0_231
	global_store_dwordx4 v[136:137], v[102:105], off offset:512 nt
	global_store_dwordx4 v[136:137], v[98:101], off offset:528 nt

.LBB0_236:
	s_add_u32 s54, s30, s62
	s_addc_u32 s55, s31, s63
	v_ashrrev_i32_e32 v139, 31, v138
	v_lshl_add_u64 v[140:141], s[54:55], 0, v[174:175]
	v_lshlrev_b64 v[138:139], 12, v[138:139]
	v_lshl_add_u64 v[138:139], v[140:141], 0, v[138:139]
	v_lshl_add_u64 v[138:139], v[138:139], 0, v[132:133]
	v_cmp_ne_u64_e32 vcc, 0, v[136:137]
	v_cvt_pk_bf16_f32 v140, v94, v95
	v_cvt_pk_bf16_f32 v141, v96, v97
	v_cvt_pk_bf16_f32 v142, v90, v91
	v_cvt_pk_bf16_f32 v143, v92, v93
	global_store_dwordx4 v[138:139], v[140:143], off
	s_and_saveexec_b64 s[62:63], vcc
	s_cbranch_execz .LBB0_238
	global_store_dwordx4 v[136:137], v[94:97], off nt
	global_store_dwordx4 v[136:137], v[90:93], off offset:16 nt
.LBB0_238:
	s_or_b64 exec, exec, s[62:63]
	v_lshl_add_u64 v[142:143], v[138:139], 0, s[60:61]
	v_cvt_pk_bf16_f32 v138, v86, v87
	v_cvt_pk_bf16_f32 v139, v88, v89
	v_cvt_pk_bf16_f32 v140, v82, v83
	v_cvt_pk_bf16_f32 v141, v84, v85
	global_store_dwordx4 v[142:143], v[138:141], off
	s_and_saveexec_b64 s[60:61], vcc
	s_cbranch_execz .LBB0_240
	global_store_dwordx4 v[136:137], v[86:89], off offset:512 nt
	global_store_dwordx4 v[136:137], v[82:85], off offset:528 nt

.LBB0_244:
	s_add_u32 s54, s30, s62
	s_addc_u32 s55, s31, s63
	v_ashrrev_i32_e32 v139, 31, v138
	v_lshl_add_u64 v[140:141], s[54:55], 0, v[174:175]
	v_lshlrev_b64 v[138:139], 12, v[138:139]
	v_lshl_add_u64 v[138:139], v[140:141], 0, v[138:139]
	v_lshl_add_u64 v[138:139], v[138:139], 0, v[134:135]
	v_cmp_ne_u64_e32 vcc, 0, v[136:137]
	v_cvt_pk_bf16_f32 v140, v78, v79
	v_cvt_pk_bf16_f32 v141, v80, v81
	v_cvt_pk_bf16_f32 v142, v74, v75
	v_cvt_pk_bf16_f32 v143, v76, v77
	global_store_dwordx4 v[138:139], v[140:143], off
	s_and_saveexec_b64 s[62:63], vcc
	s_cbranch_execz .LBB0_246
	global_store_dwordx4 v[136:137], v[78:81], off nt
	global_store_dwordx4 v[136:137], v[74:77], off offset:16 nt
.LBB0_246:
	s_or_b64 exec, exec, s[62:63]
	v_lshl_add_u64 v[142:143], v[138:139], 0, s[60:61]
	v_cvt_pk_bf16_f32 v138, v70, v71
	v_cvt_pk_bf16_f32 v139, v72, v73
	v_cvt_pk_bf16_f32 v140, v66, v67
	v_cvt_pk_bf16_f32 v141, v68, v69
	global_store_dwordx4 v[142:143], v[138:141], off
	s_and_saveexec_b64 s[60:61], vcc
	s_cbranch_execz .LBB0_248
	global_store_dwordx4 v[136:137], v[70:73], off offset:512 nt
	global_store_dwordx4 v[136:137], v[66:69], off offset:528 nt

.LBB0_252:
	s_add_u32 s54, s30, s62
	s_addc_u32 s55, s31, s63
	v_ashrrev_i32_e32 v139, 31, v138
	v_lshl_add_u64 v[142:143], s[54:55], 0, v[174:175]
	v_lshlrev_b64 v[138:139], 12, v[138:139]
	v_lshl_add_u64 v[138:139], v[142:143], 0, v[138:139]
	v_lshl_add_u64 v[138:139], v[138:139], 0, v[132:133]
	v_cmp_ne_u64_e32 vcc, 0, v[136:137]
	v_cvt_pk_bf16_f32 v142, v62, v63
	v_cvt_pk_bf16_f32 v143, v64, v65
	v_cvt_pk_bf16_f32 v144, v58, v59
	v_cvt_pk_bf16_f32 v145, v60, v61
	global_store_dwordx4 v[138:139], v[142:145], off
	s_and_saveexec_b64 s[62:63], vcc
	s_cbranch_execz .LBB0_254
	global_store_dwordx4 v[136:137], v[62:65], off nt
	global_store_dwordx4 v[136:137], v[58:61], off offset:16 nt
.LBB0_254:
	s_or_b64 exec, exec, s[62:63]
	v_lshl_add_u64 v[138:139], v[138:139], 0, s[60:61]
	v_cvt_pk_bf16_f32 v142, v54, v55
	v_cvt_pk_bf16_f32 v143, v56, v57
	v_cvt_pk_bf16_f32 v144, v50, v51
	v_cvt_pk_bf16_f32 v145, v52, v53
	global_store_dwordx4 v[138:139], v[142:145], off
	s_and_saveexec_b64 s[60:61], vcc
	s_cbranch_execz .LBB0_256
	global_store_dwordx4 v[136:137], v[54:57], off offset:512 nt
	global_store_dwordx4 v[136:137], v[50:53], off offset:528 nt

.LBB0_260:
	s_add_u32 s54, s30, s62
	s_addc_u32 s55, s31, s63
	v_ashrrev_i32_e32 v139, 31, v138
	v_lshl_add_u64 v[142:143], s[54:55], 0, v[174:175]
	v_lshlrev_b64 v[138:139], 12, v[138:139]
	v_lshl_add_u64 v[138:139], v[142:143], 0, v[138:139]
	v_lshl_add_u64 v[138:139], v[138:139], 0, v[134:135]
	v_cmp_ne_u64_e32 vcc, 0, v[136:137]
	v_cvt_pk_bf16_f32 v142, v46, v47
	v_cvt_pk_bf16_f32 v143, v48, v49
	v_cvt_pk_bf16_f32 v144, v42, v43
	v_cvt_pk_bf16_f32 v145, v44, v45
	global_store_dwordx4 v[138:139], v[142:145], off
	s_and_saveexec_b64 s[62:63], vcc
	s_cbranch_execz .LBB0_262
	global_store_dwordx4 v[136:137], v[46:49], off nt
	global_store_dwordx4 v[136:137], v[42:45], off offset:16 nt
.LBB0_262:
	s_or_b64 exec, exec, s[62:63]
	v_lshl_add_u64 v[138:139], v[138:139], 0, s[60:61]
	v_cvt_pk_bf16_f32 v142, v38, v39
	v_cvt_pk_bf16_f32 v143, v40, v41
	v_cvt_pk_bf16_f32 v144, v34, v35
	v_cvt_pk_bf16_f32 v145, v36, v37
	global_store_dwordx4 v[138:139], v[142:145], off
	s_and_saveexec_b64 s[60:61], vcc
	s_cbranch_execz .LBB0_264
	global_store_dwordx4 v[136:137], v[38:41], off offset:512 nt
	global_store_dwordx4 v[136:137], v[34:37], off offset:528 nt

.LBB0_268:
	s_add_u32 s54, s30, s62
	s_addc_u32 s55, s31, s63
	v_ashrrev_i32_e32 v139, 31, v138
	v_lshl_add_u64 v[142:143], s[54:55], 0, v[174:175]
	v_lshlrev_b64 v[138:139], 12, v[138:139]
	v_lshl_add_u64 v[138:139], v[142:143], 0, v[138:139]
	v_lshl_add_u64 v[132:133], v[138:139], 0, v[132:133]
	v_cmp_ne_u64_e32 vcc, 0, v[136:137]
	v_cvt_pk_bf16_f32 v142, v30, v31
	v_cvt_pk_bf16_f32 v143, v32, v33
	v_cvt_pk_bf16_f32 v144, v26, v27
	v_cvt_pk_bf16_f32 v145, v28, v29
	global_store_dwordx4 v[132:133], v[142:145], off
	s_and_saveexec_b64 s[62:63], vcc
	s_cbranch_execz .LBB0_270
	global_store_dwordx4 v[136:137], v[30:33], off nt
	global_store_dwordx4 v[136:137], v[26:29], off offset:16 nt
.LBB0_270:
	s_or_b64 exec, exec, s[62:63]
	v_lshl_add_u64 v[132:133], v[132:133], 0, s[60:61]
	v_cvt_pk_bf16_f32 v142, v22, v23
	v_cvt_pk_bf16_f32 v143, v24, v25
	v_cvt_pk_bf16_f32 v144, v18, v19
	v_cvt_pk_bf16_f32 v145, v20, v21
	global_store_dwordx4 v[132:133], v[142:145], off
	s_and_saveexec_b64 s[60:61], vcc
	s_cbranch_execz .LBB0_272
	global_store_dwordx4 v[136:137], v[22:25], off offset:512 nt
	global_store_dwordx4 v[136:137], v[18:21], off offset:528 nt

.LBB0_276:
	s_add_u32 s12, s30, s60
	s_addc_u32 s13, s31, s61
	v_ashrrev_i32_e32 v137, 31, v136
	v_lshl_add_u64 v[130:131], s[12:13], 0, v[174:175]
	v_lshlrev_b64 v[136:137], 12, v[136:137]
	v_lshl_add_u64 v[130:131], v[130:131], 0, v[136:137]
	v_lshl_add_u64 v[130:131], v[130:131], 0, v[134:135]
	v_cmp_ne_u64_e32 vcc, 0, v[132:133]
	v_cvt_pk_bf16_f32 v134, v14, v15
	v_cvt_pk_bf16_f32 v135, v16, v17
	v_cvt_pk_bf16_f32 v136, v10, v11
	v_cvt_pk_bf16_f32 v137, v12, v13
	global_store_dwordx4 v[130:131], v[134:137], off
	s_and_saveexec_b64 s[12:13], vcc
	s_cbranch_execz .LBB0_278
	global_store_dwordx4 v[132:133], v[14:17], off nt
	global_store_dwordx4 v[132:133], v[10:13], off offset:16 nt
.LBB0_278:
	s_or_b64 exec, exec, s[12:13]
	v_lshl_add_u64 v[130:131], v[130:131], 0, s[10:11]
	v_cvt_pk_bf16_f32 v134, v6, v7
	v_cvt_pk_bf16_f32 v135, v8, v9
	v_cvt_pk_bf16_f32 v136, v2, v3
	v_cvt_pk_bf16_f32 v137, v4, v5
	global_store_dwordx4 v[130:131], v[134:137], off
	s_and_saveexec_b64 s[10:11], vcc
	s_cbranch_execz .LBB0_280
	global_store_dwordx4 v[132:133], v[6:9], off offset:512 nt
	global_store_dwordx4 v[132:133], v[2:5], off offset:528 nt

.LBB0_288:
	v_ashrrev_i32_e32 v215, 31, v214
	s_andn2_b64 vcc, exec, s[10:11]
	v_lshlrev_b64 v[214:215], 12, v[214:215]
	s_cbranch_vccnz .LBB0_292
	s_add_u32 s10, s30, s62
	v_pk_mul_f32 v[128:129], v[128:129], v[160:161]
	s_addc_u32 s11, s31, 0
	v_pk_fma_f32 v[124:125], v[124:125], v[156:157], v[128:129]
	v_lshl_add_u64 v[128:129], s[10:11], 0, v[214:215]
	v_lshl_add_u64 v[128:129], v[128:129], 0, v[194:195]
	v_lshl_add_u64 v[128:129], v[128:129], 0, v[182:183]
	v_pk_fma_f32 v[122:123], v[122:123], v[154:155], v[216:217]
	v_lshl_add_u64 v[128:129], v[128:129], 0, v[178:179]
	v_cvt_pk_bf16_f32 v216, v162, v163
	v_cvt_pk_bf16_f32 v217, v164, v165
	global_store_dwordx2 v[128:129], v[216:217], off
	v_cvt_pk_bf16_f32 v216, v122, v123
	v_cvt_pk_bf16_f32 v217, v124, v125
	global_store_dwordx2 v[128:129], v[216:217], off offset:2048
	s_and_saveexec_b64 s[10:11], s[12:13]
	s_cbranch_execz .LBB0_291
	s_lshl_b32 s26, s49, 2
	v_lshl_add_u64 v[128:129], v[210:211], 0, s[26:27]
	v_lshlrev_b32_e32 v174, 2, v196
	v_lshl_add_u64 v[128:129], v[128:129], 0, v[174:175]
	global_store_dwordx4 v[128:129], v[162:165], off nt
	global_store_dwordx4 v[128:129], v[122:125], off offset:128 nt

.LBB0_294:
	s_andn2_b64 vcc, exec, s[60:61]
	s_cbranch_vccnz .LBB0_298
	s_add_u32 s56, s30, s94
	s_addc_u32 s57, s31, 0
	v_lshl_add_u64 v[122:123], s[56:57], 0, v[214:215]
	v_lshl_add_u64 v[122:123], v[122:123], 0, s[42:43]
	v_lshl_add_u64 v[122:123], v[122:123], 0, v[180:181]
	v_lshl_add_u64 v[128:129], v[122:123], 0, v[176:177]
	v_cvt_pk_bf16_f32 v122, v118, v119
	v_cvt_pk_bf16_f32 v123, v120, v121
	v_cvt_pk_bf16_f32 v124, v114, v115
	v_cvt_pk_bf16_f32 v125, v116, v117
	global_store_dwordx4 v[128:129], v[122:125], off
	s_and_saveexec_b64 s[60:61], s[12:13]
	s_cbranch_execz .LBB0_297
	s_lshl_b32 s26, s63, 2
	v_lshl_add_u64 v[122:123], v[210:211], 0, s[26:27]
	v_lshlrev_b32_e32 v174, 2, v192
	v_lshl_add_u64 v[122:123], v[122:123], 0, v[174:175]
	global_store_dwordx4 v[122:123], v[118:121], off nt
	global_store_dwordx4 v[122:123], v[114:117], off offset:16 nt

.LBB0_309:
	s_add_u32 s56, s30, s62
	v_pk_mul_f32 v[112:113], v[112:113], v[152:153]
	s_addc_u32 s57, s31, 0
	v_pk_fma_f32 v[108:109], v[108:109], v[148:149], v[112:113]
	v_lshl_add_u64 v[112:113], s[56:57], 0, v[110:111]
	v_lshl_add_u64 v[112:113], v[112:113], 0, v[194:195]
	v_lshl_add_u64 v[112:113], v[112:113], 0, v[188:189]
	v_pk_fma_f32 v[106:107], v[106:107], v[146:147], v[124:125]
	v_lshl_add_u64 v[112:113], v[112:113], 0, v[178:179]
	v_cvt_pk_bf16_f32 v122, v114, v115
	v_cvt_pk_bf16_f32 v123, v116, v117
	global_store_dwordx2 v[112:113], v[122:123], off
	v_cvt_pk_bf16_f32 v122, v106, v107
	v_cvt_pk_bf16_f32 v123, v108, v109
	global_store_dwordx2 v[112:113], v[122:123], off offset:2048
	s_and_saveexec_b64 s[60:61], s[14:15]
	s_cbranch_execz .LBB0_311
	s_lshl_b32 s26, s49, 2
	v_lshl_add_u64 v[112:113], v[118:119], 0, s[26:27]
	v_lshlrev_b32_e32 v174, 2, v196
	v_lshl_add_u64 v[112:113], v[112:113], 0, v[174:175]
	global_store_dwordx4 v[112:113], v[114:117], off nt
	global_store_dwordx4 v[112:113], v[106:109], off offset:128 nt

.LBB0_313:
	s_add_u32 s56, s30, s94
	s_addc_u32 s57, s31, 0
	v_lshl_add_u64 v[106:107], s[56:57], 0, v[110:111]
	v_lshl_add_u64 v[106:107], v[106:107], 0, s[42:43]
	v_lshl_add_u64 v[106:107], v[106:107], 0, v[186:187]
	v_lshl_add_u64 v[110:111], v[106:107], 0, v[176:177]
	v_cvt_pk_bf16_f32 v106, v102, v103
	v_cvt_pk_bf16_f32 v107, v104, v105
	v_cvt_pk_bf16_f32 v108, v98, v99
	v_cvt_pk_bf16_f32 v109, v100, v101
	global_store_dwordx4 v[110:111], v[106:109], off
	s_and_saveexec_b64 s[60:61], s[14:15]
	s_cbranch_execz .LBB0_315
	s_lshl_b32 s26, s63, 2
	v_lshl_add_u64 v[106:107], v[118:119], 0, s[26:27]
	v_lshlrev_b32_e32 v174, 2, v192
	v_lshl_add_u64 v[106:107], v[106:107], 0, v[174:175]
	global_store_dwordx4 v[106:107], v[102:105], off nt
	global_store_dwordx4 v[106:107], v[98:101], off offset:16 nt

.LBB0_325:
	s_add_u32 s56, s30, s62
	v_pk_mul_f32 v[96:97], v[96:97], v[144:145]
	s_addc_u32 s57, s31, 0
	v_pk_fma_f32 v[92:93], v[92:93], v[140:141], v[96:97]
	v_lshl_add_u64 v[96:97], s[56:57], 0, v[94:95]
	v_lshl_add_u64 v[96:97], v[96:97], 0, v[194:195]
	v_lshl_add_u64 v[96:97], v[96:97], 0, v[182:183]
	v_pk_fma_f32 v[90:91], v[90:91], v[138:139], v[108:109]
	v_lshl_add_u64 v[96:97], v[96:97], 0, v[178:179]
	v_cvt_pk_bf16_f32 v106, v98, v99
	v_cvt_pk_bf16_f32 v107, v100, v101
	global_store_dwordx2 v[96:97], v[106:107], off
	v_cvt_pk_bf16_f32 v106, v90, v91
	v_cvt_pk_bf16_f32 v107, v92, v93
	global_store_dwordx2 v[96:97], v[106:107], off offset:2048
	s_and_saveexec_b64 s[60:61], s[14:15]
	s_cbranch_execz .LBB0_327
	s_lshl_b32 s26, s49, 2
	v_lshl_add_u64 v[96:97], v[102:103], 0, s[26:27]
	v_lshlrev_b32_e32 v174, 2, v196
	v_lshl_add_u64 v[96:97], v[96:97], 0, v[174:175]
	global_store_dwordx4 v[96:97], v[98:101], off nt
	global_store_dwordx4 v[96:97], v[90:93], off offset:128 nt

.LBB0_329:
	s_add_u32 s56, s30, s94
	s_addc_u32 s57, s31, 0
	v_lshl_add_u64 v[90:91], s[56:57], 0, v[94:95]
	v_lshl_add_u64 v[90:91], v[90:91], 0, s[42:43]
	v_lshl_add_u64 v[90:91], v[90:91], 0, v[180:181]
	v_lshl_add_u64 v[94:95], v[90:91], 0, v[176:177]
	v_cvt_pk_bf16_f32 v90, v86, v87
	v_cvt_pk_bf16_f32 v91, v88, v89
	v_cvt_pk_bf16_f32 v92, v82, v83
	v_cvt_pk_bf16_f32 v93, v84, v85
	global_store_dwordx4 v[94:95], v[90:93], off
	s_and_saveexec_b64 s[60:61], s[14:15]
	s_cbranch_execz .LBB0_331
	s_lshl_b32 s26, s63, 2
	v_lshl_add_u64 v[90:91], v[102:103], 0, s[26:27]
	v_lshlrev_b32_e32 v174, 2, v192
	v_lshl_add_u64 v[90:91], v[90:91], 0, v[174:175]
	global_store_dwordx4 v[90:91], v[86:89], off nt
	global_store_dwordx4 v[90:91], v[82:85], off offset:16 nt

.LBB0_339:
	s_add_u32 s56, s30, s62
	v_pk_mul_f32 v[80:81], v[80:81], v[136:137]
	s_addc_u32 s57, s31, 0
	v_pk_fma_f32 v[76:77], v[76:77], v[132:133], v[80:81]
	v_lshl_add_u64 v[80:81], s[56:57], 0, v[78:79]
	v_lshl_add_u64 v[80:81], v[80:81], 0, v[194:195]
	v_lshl_add_u64 v[80:81], v[80:81], 0, v[188:189]
	v_pk_fma_f32 v[74:75], v[74:75], v[130:131], v[92:93]
	v_lshl_add_u64 v[80:81], v[80:81], 0, v[178:179]
	v_cvt_pk_bf16_f32 v90, v82, v83
	v_cvt_pk_bf16_f32 v91, v84, v85
	global_store_dwordx2 v[80:81], v[90:91], off
	v_cvt_pk_bf16_f32 v90, v74, v75
	v_cvt_pk_bf16_f32 v91, v76, v77
	global_store_dwordx2 v[80:81], v[90:91], off offset:2048
	s_and_saveexec_b64 s[60:61], s[14:15]
	s_cbranch_execz .LBB0_341
	s_lshl_b32 s26, s49, 2
	v_lshl_add_u64 v[80:81], v[86:87], 0, s[26:27]
	v_lshlrev_b32_e32 v174, 2, v196
	v_lshl_add_u64 v[80:81], v[80:81], 0, v[174:175]
	global_store_dwordx4 v[80:81], v[82:85], off nt
	global_store_dwordx4 v[80:81], v[74:77], off offset:128 nt

.LBB0_343:
	s_add_u32 s56, s30, s94
	s_addc_u32 s57, s31, 0
	v_lshl_add_u64 v[74:75], s[56:57], 0, v[78:79]
	v_lshl_add_u64 v[74:75], v[74:75], 0, s[42:43]
	v_lshl_add_u64 v[74:75], v[74:75], 0, v[186:187]
	v_lshl_add_u64 v[78:79], v[74:75], 0, v[176:177]
	v_cvt_pk_bf16_f32 v74, v70, v71
	v_cvt_pk_bf16_f32 v75, v72, v73
	v_cvt_pk_bf16_f32 v76, v66, v67
	v_cvt_pk_bf16_f32 v77, v68, v69
	global_store_dwordx4 v[78:79], v[74:77], off
	s_and_saveexec_b64 s[60:61], s[14:15]
	s_cbranch_execz .LBB0_345
	s_lshl_b32 s26, s63, 2
	v_lshl_add_u64 v[74:75], v[86:87], 0, s[26:27]
	v_lshlrev_b32_e32 v174, 2, v192
	v_lshl_add_u64 v[74:75], v[74:75], 0, v[174:175]
	global_store_dwordx4 v[74:75], v[70:73], off nt
	global_store_dwordx4 v[74:75], v[66:69], off offset:16 nt

.LBB0_357:
	s_add_u32 s14, s30, s62
	v_pk_mul_f32 v[64:65], v[64:65], v[96:97]
	s_addc_u32 s15, s31, 0
	v_pk_fma_f32 v[60:61], v[60:61], v[92:93], v[64:65]
	v_lshl_add_u64 v[64:65], s[14:15], 0, v[62:63]
	v_lshl_add_u64 v[64:65], v[64:65], 0, v[194:195]
	v_lshl_add_u64 v[64:65], v[64:65], 0, v[182:183]
	v_pk_fma_f32 v[58:59], v[58:59], v[90:91], v[114:115]
	v_lshl_add_u64 v[64:65], v[64:65], 0, v[178:179]
	v_cvt_pk_bf16_f32 v112, v98, v99
	v_cvt_pk_bf16_f32 v113, v100, v101
	global_store_dwordx2 v[64:65], v[112:113], off
	v_cvt_pk_bf16_f32 v112, v58, v59
	v_cvt_pk_bf16_f32 v113, v60, v61
	global_store_dwordx2 v[64:65], v[112:113], off offset:2048
	s_and_saveexec_b64 s[14:15], s[8:9]
	s_cbranch_execz .LBB0_359
	s_lshl_b32 s26, s49, 2
	v_lshl_add_u64 v[64:65], v[108:109], 0, s[26:27]
	v_lshlrev_b32_e32 v174, 2, v196
	v_lshl_add_u64 v[64:65], v[64:65], 0, v[174:175]
	global_store_dwordx4 v[64:65], v[98:101], off nt
	global_store_dwordx4 v[64:65], v[58:61], off offset:128 nt

.LBB0_361:
	s_add_u32 s14, s30, s94
	s_addc_u32 s15, s31, 0
	v_lshl_add_u64 v[58:59], s[14:15], 0, v[62:63]
	v_lshl_add_u64 v[58:59], v[58:59], 0, s[42:43]
	v_lshl_add_u64 v[58:59], v[58:59], 0, v[180:181]
	v_lshl_add_u64 v[62:63], v[58:59], 0, v[176:177]
	v_cvt_pk_bf16_f32 v58, v54, v55
	v_cvt_pk_bf16_f32 v59, v56, v57
	v_cvt_pk_bf16_f32 v60, v50, v51
	v_cvt_pk_bf16_f32 v61, v52, v53
	global_store_dwordx4 v[62:63], v[58:61], off
	s_and_saveexec_b64 s[14:15], s[8:9]
	s_cbranch_execz .LBB0_363
	s_lshl_b32 s26, s63, 2
	v_lshl_add_u64 v[58:59], v[108:109], 0, s[26:27]
	v_lshlrev_b32_e32 v174, 2, v192
	v_lshl_add_u64 v[58:59], v[58:59], 0, v[174:175]
	global_store_dwordx4 v[58:59], v[54:57], off nt
	global_store_dwordx4 v[58:59], v[50:53], off offset:16 nt

.LBB0_373:
	s_add_u32 s14, s30, s62
	v_pk_mul_f32 v[48:49], v[48:49], v[88:89]
	s_addc_u32 s15, s31, 0
	v_pk_fma_f32 v[44:45], v[44:45], v[84:85], v[48:49]
	v_lshl_add_u64 v[48:49], s[14:15], 0, v[46:47]
	v_lshl_add_u64 v[48:49], v[48:49], 0, v[194:195]
	v_lshl_add_u64 v[48:49], v[48:49], 0, v[188:189]
	v_pk_fma_f32 v[42:43], v[42:43], v[82:83], v[60:61]
	v_lshl_add_u64 v[48:49], v[48:49], 0, v[178:179]
	v_cvt_pk_bf16_f32 v58, v50, v51
	v_cvt_pk_bf16_f32 v59, v52, v53
	global_store_dwordx2 v[48:49], v[58:59], off
	v_cvt_pk_bf16_f32 v58, v42, v43
	v_cvt_pk_bf16_f32 v59, v44, v45
	global_store_dwordx2 v[48:49], v[58:59], off offset:2048
	s_and_saveexec_b64 s[14:15], s[8:9]
	s_cbranch_execz .LBB0_375
	s_lshl_b32 s26, s49, 2
	v_lshl_add_u64 v[48:49], v[54:55], 0, s[26:27]
	v_lshlrev_b32_e32 v174, 2, v196
	v_lshl_add_u64 v[48:49], v[48:49], 0, v[174:175]
	global_store_dwordx4 v[48:49], v[50:53], off nt
	global_store_dwordx4 v[48:49], v[42:45], off offset:128 nt

.LBB0_377:
	s_add_u32 s14, s30, s94
	s_addc_u32 s15, s31, 0
	v_lshl_add_u64 v[42:43], s[14:15], 0, v[46:47]
	v_lshl_add_u64 v[42:43], v[42:43], 0, s[42:43]
	v_lshl_add_u64 v[42:43], v[42:43], 0, v[186:187]
	v_lshl_add_u64 v[46:47], v[42:43], 0, v[176:177]
	v_cvt_pk_bf16_f32 v42, v38, v39
	v_cvt_pk_bf16_f32 v43, v40, v41
	v_cvt_pk_bf16_f32 v44, v34, v35
	v_cvt_pk_bf16_f32 v45, v36, v37
	global_store_dwordx4 v[46:47], v[42:45], off
	s_and_saveexec_b64 s[14:15], s[8:9]
	s_cbranch_execz .LBB0_379
	s_lshl_b32 s26, s63, 2
	v_lshl_add_u64 v[42:43], v[54:55], 0, s[26:27]
	v_lshlrev_b32_e32 v174, 2, v192
	v_lshl_add_u64 v[42:43], v[42:43], 0, v[174:175]
	global_store_dwordx4 v[42:43], v[38:41], off nt
	global_store_dwordx4 v[42:43], v[34:37], off offset:16 nt

.LBB0_389:
	s_add_u32 s14, s30, s62
	v_pk_mul_f32 v[32:33], v[32:33], v[80:81]
	s_addc_u32 s15, s31, 0
	v_pk_fma_f32 v[28:29], v[28:29], v[76:77], v[32:33]
	v_lshl_add_u64 v[32:33], s[14:15], 0, v[30:31]
	v_lshl_add_u64 v[32:33], v[32:33], 0, v[194:195]
	v_lshl_add_u64 v[32:33], v[32:33], 0, v[182:183]
	v_pk_fma_f32 v[26:27], v[26:27], v[74:75], v[44:45]
	v_lshl_add_u64 v[32:33], v[32:33], 0, v[178:179]
	v_cvt_pk_bf16_f32 v42, v34, v35
	v_cvt_pk_bf16_f32 v43, v36, v37
	global_store_dwordx2 v[32:33], v[42:43], off
	v_cvt_pk_bf16_f32 v42, v26, v27
	v_cvt_pk_bf16_f32 v43, v28, v29
	global_store_dwordx2 v[32:33], v[42:43], off offset:2048
	s_and_saveexec_b64 s[14:15], s[8:9]
	s_cbranch_execz .LBB0_391
	s_lshl_b32 s26, s49, 2
	v_lshl_add_u64 v[32:33], v[38:39], 0, s[26:27]
	v_lshlrev_b32_e32 v174, 2, v196
	v_lshl_add_u64 v[32:33], v[32:33], 0, v[174:175]
	global_store_dwordx4 v[32:33], v[34:37], off nt
	global_store_dwordx4 v[32:33], v[26:29], off offset:128 nt

.LBB0_393:
	s_add_u32 s14, s30, s94
	s_addc_u32 s15, s31, 0
	v_lshl_add_u64 v[26:27], s[14:15], 0, v[30:31]
	v_lshl_add_u64 v[26:27], v[26:27], 0, s[42:43]
	v_lshl_add_u64 v[26:27], v[26:27], 0, v[180:181]
	v_lshl_add_u64 v[30:31], v[26:27], 0, v[176:177]
	v_cvt_pk_bf16_f32 v26, v22, v23
	v_cvt_pk_bf16_f32 v27, v24, v25
	v_cvt_pk_bf16_f32 v28, v18, v19
	v_cvt_pk_bf16_f32 v29, v20, v21
	global_store_dwordx4 v[30:31], v[26:29], off
	s_and_saveexec_b64 s[14:15], s[8:9]
	s_cbranch_execz .LBB0_395
	s_lshl_b32 s26, s63, 2
	v_lshl_add_u64 v[26:27], v[38:39], 0, s[26:27]
	v_lshlrev_b32_e32 v174, 2, v192
	v_lshl_add_u64 v[26:27], v[26:27], 0, v[174:175]
	global_store_dwordx4 v[26:27], v[22:25], off nt
	global_store_dwordx4 v[26:27], v[18:21], off offset:16 nt

.LBB0_406:
	s_add_u32 s12, s30, s62
	v_pk_mul_f32 v[16:17], v[16:17], v[72:73]
	s_addc_u32 s13, s31, 0
	v_pk_fma_f32 v[12:13], v[12:13], v[68:69], v[16:17]
	v_lshl_add_u64 v[16:17], s[12:13], 0, v[14:15]
	v_lshl_add_u64 v[16:17], v[16:17], 0, v[194:195]
	v_lshl_add_u64 v[16:17], v[16:17], 0, v[188:189]
	v_pk_fma_f32 v[10:11], v[10:11], v[66:67], v[28:29]
	v_lshl_add_u64 v[16:17], v[16:17], 0, v[178:179]
	v_cvt_pk_bf16_f32 v26, v18, v19
	v_cvt_pk_bf16_f32 v27, v20, v21
	global_store_dwordx2 v[16:17], v[26:27], off
	v_cvt_pk_bf16_f32 v26, v10, v11
	v_cvt_pk_bf16_f32 v27, v12, v13
	global_store_dwordx2 v[16:17], v[26:27], off offset:2048
	s_and_saveexec_b64 s[12:13], s[8:9]
	s_cbranch_execz .LBB0_408
	s_lshl_b32 s26, s49, 2
	v_lshl_add_u64 v[16:17], v[22:23], 0, s[26:27]
	v_lshlrev_b32_e32 v174, 2, v196
	v_lshl_add_u64 v[16:17], v[16:17], 0, v[174:175]
	global_store_dwordx4 v[16:17], v[18:21], off nt
	global_store_dwordx4 v[16:17], v[10:13], off offset:128 nt

.LBB0_410:
	s_add_u32 s10, s30, s94
	s_addc_u32 s11, s31, 0
	v_lshl_add_u64 v[10:11], s[10:11], 0, v[14:15]
	v_lshl_add_u64 v[10:11], v[10:11], 0, s[42:43]
	v_lshl_add_u64 v[10:11], v[10:11], 0, v[186:187]
	v_lshl_add_u64 v[14:15], v[10:11], 0, v[176:177]
	v_cvt_pk_bf16_f32 v10, v6, v7
	v_cvt_pk_bf16_f32 v11, v8, v9
	v_cvt_pk_bf16_f32 v12, v2, v3
	v_cvt_pk_bf16_f32 v13, v4, v5
	global_store_dwordx4 v[14:15], v[10:13], off
	s_and_saveexec_b64 s[10:11], s[8:9]
	s_cbranch_execz .LBB0_412
	s_lshl_b32 s26, s63, 2
	v_lshl_add_u64 v[10:11], v[22:23], 0, s[26:27]
	v_lshlrev_b32_e32 v174, 2, v192
	v_lshl_add_u64 v[10:11], v[10:11], 0, v[174:175]
	global_store_dwordx4 v[10:11], v[6:9], off nt
	global_store_dwordx4 v[10:11], v[2:5], off offset:16 nt
